# drop the agent-scope L1 invalidate at the two workgroup-local phase hand-offs (workgroup-scope seam: same CU produced the data)
# baseline (speedup 1.0000x reference)
; __device__ __forceinline__ int launder_i(int v) { asm volatile("" : "+s"(v)); return v; }
; #define GSYNC() do { xcd_barrier(xbar); for (int r_ = 0; r_ < REP_SYNC; ++r_) xcd_barrier(xbar); } while (0)
; __global__ void __launch_bounds__(NWAVES * 64, 2) fwd_kernel(KArgs a) {
;     ...
;         if (launder_i(G) != 256) { GSYNC(); }
;         else {
;             asm volatile("s_waitcnt vmcnt(0)" ::: "memory"); __syncthreads();
;             if (threadIdx.x == 0) { __builtin_amdgcn_fence(__ATOMIC_ACQUIRE, "agent"); asm volatile("s_waitcnt vmcnt(0)" ::: "memory"); }
;             __syncthreads();
;         }
.LBB0_949:
	s_and_b64 vcc, exec, s[0:1]
	s_cbranch_vccz .LBB0_953
	s_waitcnt vmcnt(0)
	s_barrier
	s_mov_b64 s[0:1], exec
	v_readlane_b32 s2, v254, 4
	v_readlane_b32 s3, v254, 5
	s_and_b64 s[2:3], s[0:1], s[2:3]
	s_mov_b64 exec, s[2:3]
	s_cbranch_execz .LBB0_952
	s_waitcnt vmcnt(0)
	s_waitcnt vmcnt(0)

; __global__ void __launch_bounds__(NWAVES * 64, 2) fwd_kernel(KArgs a) {
;     ...
;         asm volatile("s_waitcnt vmcnt(0)" ::: "memory"); __syncthreads();
;         if (threadIdx.x == 0) { __builtin_amdgcn_fence(__ATOMIC_ACQUIRE, "agent"); asm volatile("s_waitcnt vmcnt(0)" ::: "memory"); }
;         __syncthreads();
.LBB0_1004:
	s_waitcnt vmcnt(0)
	s_barrier
	s_mov_b64 s[0:1], exec
	v_readlane_b32 s2, v254, 4
	v_readlane_b32 s3, v254, 5
	s_and_b64 s[2:3], s[0:1], s[2:3]
	s_mov_b64 exec, s[2:3]
	s_cbranch_execz .LBB0_1006
	s_waitcnt vmcnt(0)
	s_waitcnt vmcnt(0)
